# v14 + hgrn forget-gate rows touched one chunk further ahead by a dword load (L2 warm-up), counted vmcnt adjusted
# speedup vs baseline: 1.0124x; 1.0113x over previous
.LBB0_481:
	s_cmp_ge_u32 s47, s101
	s_cbranch_scc1 .Lhs_suspend
	v_mov_b32_e32 v36, v68
	s_andn2_b64 vcc, exec, s[94:95]
	v_lshrrev_b32_e32 v37, 3, v36
	v_and_or_b32 v40, v37, 7, s70
	v_and_b32_e32 v41, 7, v36
	v_lshlrev_b32_e32 v36, 8, v40
	v_lshlrev_b32_e32 v37, 5, v41
	v_add3_u32 v36, s69, v36, v37
	ds_read_b128 v[44:47], v36
	ds_read_b128 v[36:39], v36 offset:16
	v_mul_lo_u32 v110, v40, s61
	v_lshlrev_b32_e32 v111, 4, v41
	v_cndmask_b32_e64 v40, 0, 1, s[94:95]
	v_lshlrev_b32_e32 v109, 3, v41
	v_add3_u32 v108, 0, v110, v111
	v_cmp_ne_u32_e64 s[34:35], 1, v40
	v_mov_b32_e32 v43, 0
	v_mov_b32_e32 v42, 0
	v_mov_b32_e32 v41, 0
	v_mov_b32_e32 v40, 0
	v_mov_b32_e32 v51, 0
	v_mov_b32_e32 v50, 0
	v_mov_b32_e32 v49, 0
	v_mov_b32_e32 v48, 0
	s_waitcnt vmcnt(9)
	ds_write_b128 v108, v[12:15] offset:27648
	s_cbranch_vccnz .LBB0_483
	v_lshl_add_u32 v40, v109, 2, s66
	ds_read_b128 v[48:51], v40
	ds_read_b128 v[40:43], v40 offset:16

.LBB0_488:
	v_mov_b32_e32 v36, v68
	s_cmpk_lt_u32 s47, 0x42
	v_lshrrev_b32_e32 v37, 3, v36
	v_and_or_b32 v37, v37, 7, s70
	v_lshlrev_b32_e32 v36, 4, v36
	s_cselect_b64 s[54:55], -1, 0
	s_cmpk_gt_u32 s47, 0x41
	v_mul_lo_u32 v37, v37, s61
	v_and_b32_e32 v36, 0x70, v36
	v_readlane_b32 s4, v255, 7
	s_cselect_b64 s[60:61], -1, 0
	s_movk_i32 s72, 0x90
	v_add3_u32 v36, s4, v37, v36
	s_and_b64 vcc, exec, s[60:61]
	s_waitcnt vmcnt(5)
	ds_write_b128 v36, v[20:23]
	s_waitcnt lgkmcnt(0)
	s_barrier
	s_cbranch_vccnz .Lhg_skipA
	s_lshl_b32 s4, s47, 6
	s_add_i32 s36, s4, 0xffffff80
	s_sub_i32 s37, 0x107f, s4
	v_mov_b32_e32 v4, v68
	s_and_b64 s[4:5], s[6:7], exec
	s_cselect_b32 s4, s36, s37
	v_lshrrev_b32_e32 v5, 3, v4
	s_add_i32 s4, s4, s76
	v_and_or_b32 v5, v5, 7, s70
	s_cmp_eq_u32 s47, 0
	v_sub_u32_e32 v6, 0, v5
	s_cselect_b32 s4, s2, s4
	v_cndmask_b32_e64 v5, v6, v5, s[6:7]
	v_add_u32_e32 v5, s4, v5
	s_and_b64 s[4:5], s[6:7], exec
	s_cselect_b32 s5, 0, -1
	s_mov_b32 s4, 0x70000
	s_xor_b32 s4, s4, s5
	s_sub_u32 s4, s4, s5
	v_mul_u32_u24_e32 v5, 0xe00, v5
	v_lshlrev_b32_e32 v4, 3, v4
	v_and_or_b32 v4, v4, 56, v5
	v_ashrrev_i32_e32 v5, 31, v4
	v_lshl_add_u64 v[12:13], v[4:5], 1, s[58:59]
	s_lshl_b32 s48, s73, 1
	v_lshl_add_u64 v[4:5], v[12:13], 0, s[48:49]
	v_lshl_add_u64 v[176:177], v[4:5], 0, s[4:5]
	global_load_dwordx4 v[4:7], v[4:5], off offset:1536
	s_nop 0
	global_load_dwordx4 v[8:11], v[12:13], off
	s_nop 0
	global_load_dwordx4 v[12:15], v[12:13], off offset:512
	global_load_dword v178, v[176:177], off offset:1536

.LBB0_508:
	v_add_u32_e32 v109, v72, v64
	v_add_u32_e32 v108, v73, v64
	ds_read_b64_tr_b16 v[40:41], v104 offset:27648
	ds_read_b64_tr_b16 v[42:43], v104 offset:28224
	v_exp_f32_e32 v60, v118
	v_exp_f32_e32 v61, v119
	ds_read_b128 v[44:47], v109 offset:36864
	v_exp_f32_e32 v62, v120
	v_exp_f32_e32 v63, v121
	ds_read_b128 v[36:39], v108 offset:36864
	s_waitcnt lgkmcnt(1)
	v_mfma_f32_16x16x32_bf16 v[44:47], v[40:43], v[44:47], 0
	ds_read_b64_tr_b16 v[48:49], v104 offset:18432
	ds_read_b64_tr_b16 v[50:51], v104 offset:19008
	ds_read_b64_tr_b16 v[52:53], v104 offset:32256
	v_pk_mul_f32 v[30:31], v[30:31], v[62:63]
	v_pk_mul_f32 v[28:29], v[28:29], v[60:61]
	s_waitcnt lgkmcnt(3)
	v_mfma_f32_16x16x32_bf16 v[36:39], v[40:43], v[36:39], 0
	ds_read_b64_tr_b16 v[40:41], v106 offset:27648
	ds_read_b64_tr_b16 v[42:43], v106 offset:28224
	ds_read_b64_tr_b16 v[56:57], v107 offset:27648
	ds_read_b64_tr_b16 v[58:59], v107 offset:28224
	ds_read_b64_tr_b16 v[54:55], v104 offset:32832
	v_pk_mul_f32 v[34:35], v[34:35], v[62:63]
	v_pk_mul_f32 v[32:33], v[32:33], v[60:61]
	s_waitcnt lgkmcnt(3)
	v_mfma_f32_16x16x32_bf16 v[28:31], v[48:51], v[40:43], v[28:31]
	v_add_u32_e32 v113, v72, v74
	v_add_u32_e32 v112, v73, v74
	v_readlane_b32 s4, v255, 10
	s_waitcnt lgkmcnt(1)
	v_mfma_f32_16x16x32_bf16 v[40:43], v[48:51], v[56:59], v[32:35]
	s_nop 2
	ds_read_b128 v[32:35], v109 offset:36928
	ds_read_b64_tr_b16 v[48:49], v104 offset:23616
	ds_read_b128 v[56:59], v108 offset:36928
	s_and_b64 vcc, exec, s[34:35]
	s_waitcnt lgkmcnt(2)
	v_mfma_f32_16x16x32_bf16 v[60:63], v[52:55], v[32:35], v[44:47]
	s_nop 2
	ds_read_b64_tr_b16 v[46:47], v104 offset:23040
	ds_read_b64_tr_b16 v[32:33], v106 offset:32256
	s_waitcnt lgkmcnt(2)
	v_mfma_f32_16x16x32_bf16 v[36:39], v[52:55], v[56:59], v[36:39]
	ds_read_b64_tr_b16 v[34:35], v106 offset:32832
	ds_read_b64_tr_b16 v[50:51], v107 offset:32256
	ds_read_b64_tr_b16 v[52:53], v107 offset:32832
	ds_read_b128 v[54:57], v105 offset:46080
	s_waitcnt lgkmcnt(3)
	v_mfma_f32_16x16x32_bf16 v[32:35], v[46:49], v[32:35], v[28:31]
	s_waitcnt lgkmcnt(1)
	v_mfma_f32_16x16x32_bf16 v[28:31], v[46:49], v[50:53], v[40:43]
	s_nop 2
	ds_read_b128 v[40:43], v109 offset:9216
	ds_read_b128 v[44:47], v108 offset:9216
	ds_read_b128 v[48:51], v105 offset:46144
	s_waitcnt lgkmcnt(1)
	v_mfma_f32_16x16x32_bf16 v[36:39], v[54:57], v[44:47], v[36:39]
	ds_read_b128 v[44:47], v109 offset:9280
	v_mfma_f32_16x16x32_bf16 v[40:43], v[54:57], v[40:43], v[60:63]
	s_waitcnt lgkmcnt(0)
	v_mfma_f32_16x16x32_bf16 v[40:43], v[48:51], v[44:47], v[40:43]
	ds_read_b128 v[44:47], v108 offset:9280
	s_waitcnt lgkmcnt(0)
	v_mfma_f32_16x16x32_bf16 v[36:39], v[48:51], v[44:47], v[36:39]
	v_cvt_pk_bf16_f32 v44, v32, v33
	v_cvt_pk_bf16_f32 v45, v34, v35
	ds_write_b64 v113, v[44:45] offset:55296
	v_cvt_pk_bf16_f32 v44, v28, v29
	v_cvt_pk_bf16_f32 v45, v30, v31
	ds_write_b64 v112, v[44:45] offset:55296
	v_add_u32_e32 v44, s48, v75
	v_lshl_or_b32 v180, v44, 10, v76
	v_cvt_pk_bf16_f32 v40, v40, v41
	v_cvt_pk_bf16_f32 v41, v42, v43
	v_lshl_add_u64 v[42:43], v[180:181], 1, s[92:93]
	global_store_dwordx2 v[42:43], v[40:41], off
	v_add_u32_e32 v40, s48, v77
	v_lshl_or_b32 v180, v40, 10, v76
	v_cvt_pk_bf16_f32 v36, v36, v37
	v_cvt_pk_bf16_f32 v37, v38, v39
	v_lshl_add_u64 v[38:39], v[180:181], 1, s[92:93]
	global_store_dwordx2 v[38:39], v[36:37], off
	v_mov_b32_e32 v36, v68
	s_waitcnt lgkmcnt(0)
	s_barrier
	v_mov_b32_e32 v43, 0
	v_lshrrev_b32_e32 v37, 3, v36
	v_and_or_b32 v40, v37, 7, s70
	v_and_b32_e32 v41, 7, v36
	v_lshlrev_b32_e32 v36, 8, v40
	v_lshlrev_b32_e32 v37, 5, v41
	v_add3_u32 v36, s4, v36, v37
	ds_read_b128 v[44:47], v36
	ds_read_b128 v[36:39], v36 offset:16
	v_mul_lo_u32 v116, v40, s72
	v_lshlrev_b32_e32 v117, 4, v41
	v_lshlrev_b32_e32 v115, 3, v41
	v_add3_u32 v114, 0, v116, v117
	v_mov_b32_e32 v42, 0
	v_mov_b32_e32 v41, 0
	v_mov_b32_e32 v40, 0
	v_mov_b32_e32 v51, 0
	v_mov_b32_e32 v50, 0
	v_mov_b32_e32 v49, 0
	v_mov_b32_e32 v48, 0
	s_waitcnt vmcnt(9)
	ds_write_b128 v114, v[24:27] offset:27648
	s_cbranch_vccnz .LBB0_510
	v_lshl_add_u32 v40, v115, 2, s62
	ds_read_b128 v[48:51], v40
	ds_read_b128 v[40:43], v40 offset:16

.LBB0_515:
	s_or_b32 s40, s47, 1
	s_cmpk_lt_u32 s40, 0x43
	s_cselect_b64 s[34:35], -1, 0
	s_and_b64 vcc, exec, s[34:35]
	s_cbranch_vccz .LBB0_517
	v_mov_b32_e32 v36, v68
	v_readlane_b32 s4, v255, 7
	v_lshrrev_b32_e32 v37, 3, v36
	v_and_or_b32 v37, v37, 7, s70
	v_lshlrev_b32_e32 v36, 4, v36
	v_mul_lo_u32 v37, v37, s72
	v_and_b32_e32 v36, 0x70, v36
	v_add3_u32 v36, s4, v37, v36
	s_waitcnt vmcnt(5)
	ds_write_b128 v36, v[4:7]
.LBB0_517:
	s_andn2_b64 vcc, exec, s[54:55]
	s_waitcnt lgkmcnt(0)
	s_barrier
	s_cbranch_vccnz .Lhg_skipB
	s_lshl_b32 s4, s40, 6
	s_add_i32 s41, s4, 0xffffff80
	s_sub_i32 s48, 0x107f, s4
	v_mov_b32_e32 v16, v68
	s_and_b64 s[4:5], s[6:7], exec
	s_cselect_b32 s4, s41, s48
	v_lshrrev_b32_e32 v17, 3, v16
	s_add_i32 s4, s4, s76
	v_and_or_b32 v17, v17, 7, s70
	s_cmp_eq_u32 s47, 0
	v_sub_u32_e32 v18, 0, v17
	s_cselect_b32 s4, s74, s4
	v_cndmask_b32_e64 v17, v18, v17, s[6:7]
	v_add_u32_e32 v17, s4, v17
	s_and_b64 s[4:5], s[6:7], exec
	s_cselect_b32 s5, 0, -1
	s_mov_b32 s4, 0x70000
	s_xor_b32 s4, s4, s5
	s_sub_u32 s4, s4, s5
	v_mul_u32_u24_e32 v17, 0xe00, v17
	v_lshlrev_b32_e32 v16, 3, v16
	v_and_or_b32 v16, v16, 56, v17
	v_ashrrev_i32_e32 v17, 31, v16
	v_lshl_add_u64 v[24:25], v[16:17], 1, s[58:59]
	s_lshl_b32 s48, s73, 1
	v_lshl_add_u64 v[16:17], v[24:25], 0, s[48:49]
	v_lshl_add_u64 v[176:177], v[16:17], 0, s[4:5]
	global_load_dwordx4 v[20:23], v[16:17], off offset:1536
	s_nop 0
	global_load_dwordx4 v[16:19], v[24:25], off
	s_nop 0
	global_load_dwordx4 v[24:27], v[24:25], off offset:512
	global_load_dword v178, v[176:177], off offset:1536
